# G/J gated-residual epilogue: second load batch software-pipelined behind the first batch's stores (on top of F epilogue rewrite, local barriers, qk rewrite)
# baseline (speedup 1.0000x reference)
; DI int otid() { int t = threadIdx.x; asm volatile("" : "+v"(t)); return t; }
; DI void gemm_res_tile_big(const bf16_t* A, int lda, const bf16_t* Bt, int K, const float* __restrict__ xin, float* __restrict__ xout,
;                           const float* __restrict__ gate, int mt, int nt, char* smem) {
;     ...
;     const int tid = otid();
;     stage_half(st, acc, h, tid);
;     __syncthreads();
;     const int r = tid >> 5, ch = tid & 31;
;     const float4 g = *(const float4*)(gate + (size_t)b * 6144 + n0 + ch * 4);
; #pragma unroll 4
;     for (int ps = 0; ps < 16; ++ps) {
;       const int row = ps * 8 + r;
;       const float4 a = *(const float4*)(st + row * 132 + ch * 4);
;       const size_t off = (size_t)(m0 + h * 128 + row) * 1024 + n0 + ch * 4;
;       const float4 xi = *(const float4*)(xin + off);
;       float4 o; o.x = xi.x + g.x * a.x; o.y = xi.y + g.y * a.y; o.z = xi.z + g.z * a.z; o.w = xi.w + g.w * a.w;
;       *(float4*)(xout + off) = o;
;     }
;     __syncthreads();
.LBB0_1122:
	v_lshrrev_b32_e32 v215, 5, v216
	v_mul_u32_u24_e32 v182, 0x210, v215
	v_and_b32_e32 v215, 31, v216
	v_lshl_add_u32 v182, v215, 4, v182
	v_lshlrev_b32_e32 v184, 10, v136
	v_add_u32_e32 v184, v184, v144
	v_lshlrev_b32_e32 v184, 2, v184
	v_mov_b32_e32 v214, v184
	global_load_dwordx4 v[158:161], v184, s[24:25]
	s_nop 0
	v_add_u32_e32 v184, 0x8000, v184
	global_load_dwordx4 v[162:165], v184, s[24:25]
	s_nop 0
	v_add_u32_e32 v184, 0x8000, v184
	global_load_dwordx4 v[166:169], v184, s[24:25]
	s_nop 0
	v_add_u32_e32 v184, 0x8000, v184
	global_load_dwordx4 v[170:173], v184, s[24:25]
	s_nop 0
	v_add_u32_e32 v184, 0x8000, v184
	global_load_dwordx4 v[174:177], v184, s[24:25]
	s_nop 0
	v_add_u32_e32 v184, 0x8000, v184
	global_load_dwordx4 v[178:181], v184, s[24:25]
	s_nop 0
	v_add_u32_e32 v184, 0x8000, v184
	global_load_dwordx4 v[186:189], v184, s[24:25]
	s_nop 0
	v_add_u32_e32 v184, 0x8000, v184
	global_load_dwordx4 v[190:193], v184, s[24:25]
	s_nop 0
	v_add_u32_e32 v184, 0x8000, v184
	ds_read_b128 v[194:197], v182 offset:0
	ds_read_b128 v[198:201], v182 offset:4224
	ds_read_b128 v[202:205], v182 offset:8448
	ds_read_b128 v[210:213], v182 offset:12672
	s_waitcnt vmcnt(7) lgkmcnt(3)
	v_fma_f32 v158, v154, v194, v158
	v_fma_f32 v159, v130, v195, v159
	v_fma_f32 v160, v156, v196, v160
	v_fma_f32 v161, v132, v197, v161
	global_store_dwordx4 v214, v[158:161], s[84:85]
	s_nop 1
	v_add_u32_e32 v214, 0x8000, v214
	global_load_dwordx4 v[158:161], v184, s[24:25]
	s_nop 0
	v_add_u32_e32 v184, 0x8000, v184
	s_waitcnt vmcnt(8) lgkmcnt(2)
	v_fma_f32 v162, v154, v198, v162
	v_fma_f32 v163, v130, v199, v163
	v_fma_f32 v164, v156, v200, v164
	v_fma_f32 v165, v132, v201, v165
	global_store_dwordx4 v214, v[162:165], s[84:85]
	s_nop 1
	v_add_u32_e32 v214, 0x8000, v214
	global_load_dwordx4 v[162:165], v184, s[24:25]
	s_nop 0
	v_add_u32_e32 v184, 0x8000, v184
	s_waitcnt vmcnt(9) lgkmcnt(1)
	v_fma_f32 v166, v154, v202, v166
	v_fma_f32 v167, v130, v203, v167
	v_fma_f32 v168, v156, v204, v168
	v_fma_f32 v169, v132, v205, v169
	global_store_dwordx4 v214, v[166:169], s[84:85]
	s_nop 1
	v_add_u32_e32 v214, 0x8000, v214
	global_load_dwordx4 v[166:169], v184, s[24:25]
	s_nop 0
	v_add_u32_e32 v184, 0x8000, v184
	s_waitcnt vmcnt(10) lgkmcnt(0)
	v_fma_f32 v170, v154, v210, v170
	v_fma_f32 v171, v130, v211, v171
	v_fma_f32 v172, v156, v212, v172
	v_fma_f32 v173, v132, v213, v173
	global_store_dwordx4 v214, v[170:173], s[84:85]
	s_nop 1
	v_add_u32_e32 v214, 0x8000, v214
	global_load_dwordx4 v[170:173], v184, s[24:25]
	s_nop 0
	v_add_u32_e32 v184, 0x8000, v184
	ds_read_b128 v[194:197], v182 offset:16896
	ds_read_b128 v[198:201], v182 offset:21120
	ds_read_b128 v[202:205], v182 offset:25344
	ds_read_b128 v[210:213], v182 offset:29568
	s_waitcnt vmcnt(11) lgkmcnt(3)
	v_fma_f32 v174, v154, v194, v174
	v_fma_f32 v175, v130, v195, v175
	v_fma_f32 v176, v156, v196, v176
	v_fma_f32 v177, v132, v197, v177
	global_store_dwordx4 v214, v[174:177], s[84:85]
	s_nop 1
	v_add_u32_e32 v214, 0x8000, v214
	global_load_dwordx4 v[174:177], v184, s[24:25]
	s_nop 0
	v_add_u32_e32 v184, 0x8000, v184
	s_waitcnt vmcnt(12) lgkmcnt(2)
	v_fma_f32 v178, v154, v198, v178
	v_fma_f32 v179, v130, v199, v179
	v_fma_f32 v180, v156, v200, v180
	v_fma_f32 v181, v132, v201, v181
	global_store_dwordx4 v214, v[178:181], s[84:85]
	s_nop 1
	v_add_u32_e32 v214, 0x8000, v214
	global_load_dwordx4 v[178:181], v184, s[24:25]
	s_nop 0
	v_add_u32_e32 v184, 0x8000, v184
	s_waitcnt vmcnt(13) lgkmcnt(1)
	v_fma_f32 v186, v154, v202, v186
	v_fma_f32 v187, v130, v203, v187
	v_fma_f32 v188, v156, v204, v188
	v_fma_f32 v189, v132, v205, v189
	global_store_dwordx4 v214, v[186:189], s[84:85]
	s_nop 1
	v_add_u32_e32 v214, 0x8000, v214
	global_load_dwordx4 v[186:189], v184, s[24:25]
	s_nop 0
	v_add_u32_e32 v184, 0x8000, v184
	s_waitcnt vmcnt(14) lgkmcnt(0)
	v_fma_f32 v190, v154, v210, v190
	v_fma_f32 v191, v130, v211, v191
	v_fma_f32 v192, v156, v212, v192
	v_fma_f32 v193, v132, v213, v193
	global_store_dwordx4 v214, v[190:193], s[84:85]
	s_nop 1
	v_add_u32_e32 v214, 0x8000, v214
	global_load_dwordx4 v[190:193], v184, s[24:25]
	s_nop 0
	v_add_u32_e32 v184, 0x8000, v184
	ds_read_b128 v[194:197], v182 offset:33792
	ds_read_b128 v[198:201], v182 offset:38016
	ds_read_b128 v[202:205], v182 offset:42240
	ds_read_b128 v[210:213], v182 offset:46464
	s_waitcnt vmcnt(14) lgkmcnt(3)
	v_fma_f32 v158, v154, v194, v158
	v_fma_f32 v159, v130, v195, v159
	v_fma_f32 v160, v156, v196, v160
	v_fma_f32 v161, v132, v197, v161
	global_store_dwordx4 v214, v[158:161], s[84:85]
	s_nop 1
	v_add_u32_e32 v214, 0x8000, v214
	s_waitcnt vmcnt(13) lgkmcnt(2)
	v_fma_f32 v162, v154, v198, v162
	v_fma_f32 v163, v130, v199, v163
	v_fma_f32 v164, v156, v200, v164
	v_fma_f32 v165, v132, v201, v165
	global_store_dwordx4 v214, v[162:165], s[84:85]
	s_nop 1
	v_add_u32_e32 v214, 0x8000, v214
	s_waitcnt vmcnt(12) lgkmcnt(1)
	v_fma_f32 v166, v154, v202, v166
	v_fma_f32 v167, v130, v203, v167
	v_fma_f32 v168, v156, v204, v168
	v_fma_f32 v169, v132, v205, v169
	global_store_dwordx4 v214, v[166:169], s[84:85]
	s_nop 1
	v_add_u32_e32 v214, 0x8000, v214
	s_waitcnt vmcnt(11) lgkmcnt(0)
	v_fma_f32 v170, v154, v210, v170
	v_fma_f32 v171, v130, v211, v171
	v_fma_f32 v172, v156, v212, v172
	v_fma_f32 v173, v132, v213, v173
	global_store_dwordx4 v214, v[170:173], s[84:85]
	s_nop 1
	v_add_u32_e32 v214, 0x8000, v214
	ds_read_b128 v[194:197], v182 offset:50688
	ds_read_b128 v[198:201], v182 offset:54912
	ds_read_b128 v[202:205], v182 offset:59136
	ds_read_b128 v[210:213], v182 offset:63360
	s_waitcnt vmcnt(10) lgkmcnt(3)
	v_fma_f32 v174, v154, v194, v174
	v_fma_f32 v175, v130, v195, v175
	v_fma_f32 v176, v156, v196, v176
	v_fma_f32 v177, v132, v197, v177
	global_store_dwordx4 v214, v[174:177], s[84:85]
	s_nop 1
	v_add_u32_e32 v214, 0x8000, v214
	s_waitcnt vmcnt(9) lgkmcnt(2)
	v_fma_f32 v178, v154, v198, v178
	v_fma_f32 v179, v130, v199, v179
	v_fma_f32 v180, v156, v200, v180
	v_fma_f32 v181, v132, v201, v181
	global_store_dwordx4 v214, v[178:181], s[84:85]
	s_nop 1
	v_add_u32_e32 v214, 0x8000, v214
	s_waitcnt vmcnt(8) lgkmcnt(1)
	v_fma_f32 v186, v154, v202, v186
	v_fma_f32 v187, v130, v203, v187
	v_fma_f32 v188, v156, v204, v188
	v_fma_f32 v189, v132, v205, v189
	global_store_dwordx4 v214, v[186:189], s[84:85]
	s_nop 1
	v_add_u32_e32 v214, 0x8000, v214
	s_waitcnt vmcnt(7) lgkmcnt(0)
	v_fma_f32 v190, v154, v210, v190
	v_fma_f32 v191, v130, v211, v191
	v_fma_f32 v192, v156, v212, v192
	v_fma_f32 v193, v132, v213, v193
	global_store_dwordx4 v214, v[190:193], s[84:85]
	s_nop 1
	v_add_u32_e32 v214, 0x8000, v214
	v_mov_b32_e32 v130, v216
	s_barrier
; DI int crow(int i, int h) { return (i & 3) + 8 * (i >> 2) + 4 * h; }
; DI void stage_half(float* st, const f32x16 (&acc)[4][2], int h, int tid) {
;   const int lane = tid & 63, w = tid >> 6, wm = w >> 1, wn = w & 1, c = lane & 31, half = lane >> 5;
;   if (wm == h) {
; #pragma unroll
;     for (int mf = 0; mf < 4; ++mf)
; #pragma unroll
;       for (int nf = 0; nf < 2; ++nf)
; #pragma unroll
;         for (int i = 0; i < 16; ++i) st[(mf * 32 + crow(i, half)) * 132 + wn * 64 + nf * 32 + c] = acc[mf][nf][i];
;   }
; }
	s_nop 0
	v_and_b32_e32 v0, 0xffffff80, v130
	v_cmp_eq_u32_e32 vcc, s31, v0
	s_and_saveexec_b64 s[44:45], vcc
	s_cbranch_execz .LBB0_1125
	v_lshrrev_b32_e32 v0, 3, v130
	v_and_b32_e32 v0, 4, v0
	v_and_b32_e32 v131, 0x5f, v130
	v_mul_u32_u24_e32 v0, 0x210, v0
	v_lshl_add_u32 v0, v131, 2, v0
	ds_write2_b32 v0, v114, v98 offset1:32
	ds_write2_b32 v0, v115, v99 offset0:132 offset1:164
	v_add_u32_e32 v98, 0x400, v0
	ds_write2_b32 v98, v116, v100 offset0:8 offset1:40
	ds_write2_b32 v98, v117, v101 offset0:140 offset1:172
	v_add_u32_e32 v98, 0x1000, v0
	ds_write2_b32 v98, v118, v102 offset0:32 offset1:64
	ds_write2_b32 v98, v119, v103 offset0:164 offset1:196
	v_add_u32_e32 v98, 0x1400, v0
	ds_write2_b32 v98, v120, v104 offset0:40 offset1:72
	ds_write2_b32 v98, v121, v105 offset0:172 offset1:204
	v_add_u32_e32 v98, 0x2000, v0
	ds_write2_b32 v98, v122, v106 offset0:64 offset1:96
	ds_write2_b32 v98, v123, v107 offset0:196 offset1:228
	v_add_u32_e32 v98, 0x2400, v0
	ds_write2_b32 v98, v124, v108 offset0:72 offset1:104
	ds_write2_b32 v98, v125, v109 offset0:204 offset1:236
	v_add_u32_e32 v98, 0x3000, v0
	ds_write2_b32 v98, v126, v110 offset0:96 offset1:128
	v_add_u32_e32 v98, 0x3200, v0
	ds_write2_b32 v98, v127, v111 offset0:100 offset1:132
	v_add_u32_e32 v98, 0x3400, v0
	ds_write2_b32 v98, v128, v112 offset0:104 offset1:136
	v_add_u32_e32 v98, 0x3600, v0
	ds_write2_b32 v98, v129, v113 offset0:108 offset1:140
	v_add_u32_e32 v98, 0x4000, v0
	ds_write2_b32 v98, v82, v66 offset0:128 offset1:160
	v_add_u32_e32 v66, 0x4400, v0
	ds_write2_b32 v66, v83, v67 offset0:4 offset1:36
	ds_write2_b32 v66, v84, v68 offset0:136 offset1:168
	v_add_u32_e32 v66, 0x4800, v0
	ds_write2_b32 v66, v85, v69 offset0:12 offset1:44
	v_add_u32_e32 v66, 0x5000, v0
	ds_write2_b32 v66, v86, v70 offset0:160 offset1:192
	v_add_u32_e32 v66, 0x5400, v0
	ds_write2_b32 v66, v87, v71 offset0:36 offset1:68
	ds_write2_b32 v66, v88, v72 offset0:168 offset1:200
	v_add_u32_e32 v66, 0x5800, v0
	ds_write2_b32 v66, v89, v73 offset0:44 offset1:76
	v_add_u32_e32 v66, 0x6000, v0
	ds_write2_b32 v66, v90, v74 offset0:192 offset1:224
	v_add_u32_e32 v66, 0x6400, v0
	ds_write2_b32 v66, v91, v75 offset0:68 offset1:100
	ds_write2_b32 v66, v92, v76 offset0:200 offset1:232
	v_add_u32_e32 v66, 0x6800, v0
	ds_write2_b32 v66, v93, v77 offset0:76 offset1:108
	v_add_u32_e32 v66, 0x7200, v0
	ds_write2_b32 v66, v94, v78 offset0:96 offset1:128
	v_add_u32_e32 v66, 0x7400, v0
	ds_write2_b32 v66, v95, v79 offset0:100 offset1:132
	v_add_u32_e32 v66, 0x7600, v0
	ds_write2_b32 v66, v96, v80 offset0:104 offset1:136
	v_add_u32_e32 v66, 0x7800, v0
	ds_write2_b32 v66, v97, v81 offset0:108 offset1:140
	v_add_u32_e32 v66, 0x8400, v0
	ds_write2_b32 v66, v50, v34 offset1:32
	ds_write2_b32 v66, v51, v35 offset0:132 offset1:164
	v_add_u32_e32 v34, 0x8800, v0
	ds_write2_b32 v34, v52, v36 offset0:8 offset1:40
	ds_write2_b32 v34, v53, v37 offset0:140 offset1:172
	v_add_u32_e32 v34, 0x9400, v0
	ds_write2_b32 v34, v54, v38 offset0:32 offset1:64
	ds_write2_b32 v34, v55, v39 offset0:164 offset1:196
	v_add_u32_e32 v34, 0x9800, v0
	ds_write2_b32 v34, v56, v40 offset0:40 offset1:72
	ds_write2_b32 v34, v57, v41 offset0:172 offset1:204
	v_add_u32_e32 v34, 0xa400, v0
	ds_write2_b32 v34, v58, v42 offset0:64 offset1:96
	ds_write2_b32 v34, v59, v43 offset0:196 offset1:228
	v_add_u32_e32 v34, 0xa800, v0
	ds_write2_b32 v34, v60, v44 offset0:72 offset1:104
	ds_write2_b32 v34, v61, v45 offset0:204 offset1:236
	v_add_u32_e32 v34, 0xb400, v0
	ds_write2_b32 v34, v62, v46 offset0:96 offset1:128
	v_add_u32_e32 v34, 0xb600, v0
	ds_write2_b32 v34, v63, v47 offset0:100 offset1:132
	v_add_u32_e32 v34, 0xb800, v0
	ds_write2_b32 v34, v64, v48 offset0:104 offset1:136
	v_add_u32_e32 v34, 0xba00, v0
	ds_write2_b32 v34, v65, v49 offset0:108 offset1:140
	v_add_u32_e32 v34, 0xc400, v0
	ds_write2_b32 v34, v18, v2 offset0:128 offset1:160
	v_add_u32_e32 v2, 0xc800, v0
	ds_write2_b32 v2, v19, v3 offset0:4 offset1:36
	ds_write2_b32 v2, v20, v4 offset0:136 offset1:168
	v_add_u32_e32 v2, 0xcc00, v0
	ds_write2_b32 v2, v21, v5 offset0:12 offset1:44
	v_add_u32_e32 v2, 0xd400, v0
	ds_write2_b32 v2, v22, v6 offset0:160 offset1:192
	v_add_u32_e32 v2, 0xd800, v0
	ds_write2_b32 v2, v23, v7 offset0:36 offset1:68
	ds_write2_b32 v2, v24, v8 offset0:168 offset1:200
	v_add_u32_e32 v2, 0xdc00, v0
	ds_write2_b32 v2, v25, v9 offset0:44 offset1:76
	v_add_u32_e32 v2, 0xe400, v0
	ds_write2_b32 v2, v26, v10 offset0:192 offset1:224
	v_add_u32_e32 v2, 0xe800, v0
	ds_write2_b32 v2, v27, v11 offset0:68 offset1:100
	ds_write2_b32 v2, v28, v12 offset0:200 offset1:232
	v_add_u32_e32 v2, 0xec00, v0
	ds_write2_b32 v2, v29, v13 offset0:76 offset1:108
	v_add_u32_e32 v2, 0xf600, v0
	ds_write2_b32 v2, v30, v14 offset0:96 offset1:128
	v_add_u32_e32 v2, 0xf800, v0
	ds_write2_b32 v2, v31, v15 offset0:100 offset1:132
	v_add_u32_e32 v2, 0xfa00, v0
	v_add_u32_e32 v0, 0xfc00, v0
	ds_write2_b32 v2, v32, v16 offset0:104 offset1:136
	ds_write2_b32 v0, v33, v17 offset0:108 offset1:140

; DI int otid() { int t = threadIdx.x; asm volatile("" : "+v"(t)); return t; }
; DI void gemm_res_tile_big(const bf16_t* A, int lda, const bf16_t* Bt, int K, const float* __restrict__ xin, float* __restrict__ xout,
;                           const float* __restrict__ gate, int mt, int nt, char* smem) {
;     ...
;     const int tid = otid();
;     stage_half(st, acc, h, tid);
;     __syncthreads();
;     const int r = tid >> 5, ch = tid & 31;
;     const float4 g = *(const float4*)(gate + (size_t)b * 6144 + n0 + ch * 4);
; #pragma unroll 4
;     for (int ps = 0; ps < 16; ++ps) {
;       const int row = ps * 8 + r;
;       const float4 a = *(const float4*)(st + row * 132 + ch * 4);
;       const size_t off = (size_t)(m0 + h * 128 + row) * 1024 + n0 + ch * 4;
;       const float4 xi = *(const float4*)(xin + off);
;       float4 o; o.x = xi.x + g.x * a.x; o.y = xi.y + g.y * a.y; o.z = xi.z + g.z * a.z; o.w = xi.w + g.w * a.w;
;       *(float4*)(xout + off) = o;
;     }
;     __syncthreads();
;   }
.LBB0_1126:
	v_lshrrev_b32_e32 v215, 5, v216
	v_mul_u32_u24_e32 v182, 0x210, v215
	v_and_b32_e32 v215, 31, v216
	v_lshl_add_u32 v182, v215, 4, v182
	v_lshlrev_b32_e32 v184, 10, v12
	v_add_u32_e32 v184, v184, v8
	v_lshlrev_b32_e32 v184, 2, v184
	v_mov_b32_e32 v214, v184
	global_load_dwordx4 v[158:161], v184, s[24:25]
	s_nop 0
	v_add_u32_e32 v184, 0x8000, v184
	global_load_dwordx4 v[162:165], v184, s[24:25]
	s_nop 0
	v_add_u32_e32 v184, 0x8000, v184
	global_load_dwordx4 v[166:169], v184, s[24:25]
	s_nop 0
	v_add_u32_e32 v184, 0x8000, v184
	global_load_dwordx4 v[170:173], v184, s[24:25]
	s_nop 0
	v_add_u32_e32 v184, 0x8000, v184
	global_load_dwordx4 v[174:177], v184, s[24:25]
	s_nop 0
	v_add_u32_e32 v184, 0x8000, v184
	global_load_dwordx4 v[178:181], v184, s[24:25]
	s_nop 0
	v_add_u32_e32 v184, 0x8000, v184
	global_load_dwordx4 v[186:189], v184, s[24:25]
	s_nop 0
	v_add_u32_e32 v184, 0x8000, v184
	global_load_dwordx4 v[190:193], v184, s[24:25]
	s_nop 0
	v_add_u32_e32 v184, 0x8000, v184
	ds_read_b128 v[194:197], v182 offset:0
	ds_read_b128 v[198:201], v182 offset:4224
	ds_read_b128 v[202:205], v182 offset:8448
	ds_read_b128 v[210:213], v182 offset:12672
	s_waitcnt vmcnt(7) lgkmcnt(3)
	v_fma_f32 v158, v26, v194, v158
	v_fma_f32 v159, v2, v195, v159
	v_fma_f32 v160, v28, v196, v160
	v_fma_f32 v161, v4, v197, v161
	global_store_dwordx4 v214, v[158:161], s[84:85]
	s_nop 1
	v_add_u32_e32 v214, 0x8000, v214
	global_load_dwordx4 v[158:161], v184, s[24:25]
	s_nop 0
	v_add_u32_e32 v184, 0x8000, v184
	s_waitcnt vmcnt(8) lgkmcnt(2)
	v_fma_f32 v162, v26, v198, v162
	v_fma_f32 v163, v2, v199, v163
	v_fma_f32 v164, v28, v200, v164
	v_fma_f32 v165, v4, v201, v165
	global_store_dwordx4 v214, v[162:165], s[84:85]
	s_nop 1
	v_add_u32_e32 v214, 0x8000, v214
	global_load_dwordx4 v[162:165], v184, s[24:25]
	s_nop 0
	v_add_u32_e32 v184, 0x8000, v184
	s_waitcnt vmcnt(9) lgkmcnt(1)
	v_fma_f32 v166, v26, v202, v166
	v_fma_f32 v167, v2, v203, v167
	v_fma_f32 v168, v28, v204, v168
	v_fma_f32 v169, v4, v205, v169
	global_store_dwordx4 v214, v[166:169], s[84:85]
	s_nop 1
	v_add_u32_e32 v214, 0x8000, v214
	global_load_dwordx4 v[166:169], v184, s[24:25]
	s_nop 0
	v_add_u32_e32 v184, 0x8000, v184
	s_waitcnt vmcnt(10) lgkmcnt(0)
	v_fma_f32 v170, v26, v210, v170
	v_fma_f32 v171, v2, v211, v171
	v_fma_f32 v172, v28, v212, v172
	v_fma_f32 v173, v4, v213, v173
	global_store_dwordx4 v214, v[170:173], s[84:85]
	s_nop 1
	v_add_u32_e32 v214, 0x8000, v214
	global_load_dwordx4 v[170:173], v184, s[24:25]
	s_nop 0
	v_add_u32_e32 v184, 0x8000, v184
	ds_read_b128 v[194:197], v182 offset:16896
	ds_read_b128 v[198:201], v182 offset:21120
	ds_read_b128 v[202:205], v182 offset:25344
	ds_read_b128 v[210:213], v182 offset:29568
	s_waitcnt vmcnt(11) lgkmcnt(3)
	v_fma_f32 v174, v26, v194, v174
	v_fma_f32 v175, v2, v195, v175
	v_fma_f32 v176, v28, v196, v176
	v_fma_f32 v177, v4, v197, v177
	global_store_dwordx4 v214, v[174:177], s[84:85]
	s_nop 1
	v_add_u32_e32 v214, 0x8000, v214
	global_load_dwordx4 v[174:177], v184, s[24:25]
	s_nop 0
	v_add_u32_e32 v184, 0x8000, v184
	s_waitcnt vmcnt(12) lgkmcnt(2)
	v_fma_f32 v178, v26, v198, v178
	v_fma_f32 v179, v2, v199, v179
	v_fma_f32 v180, v28, v200, v180
	v_fma_f32 v181, v4, v201, v181
	global_store_dwordx4 v214, v[178:181], s[84:85]
	s_nop 1
	v_add_u32_e32 v214, 0x8000, v214
	global_load_dwordx4 v[178:181], v184, s[24:25]
	s_nop 0
	v_add_u32_e32 v184, 0x8000, v184
	s_waitcnt vmcnt(13) lgkmcnt(1)
	v_fma_f32 v186, v26, v202, v186
	v_fma_f32 v187, v2, v203, v187
	v_fma_f32 v188, v28, v204, v188
	v_fma_f32 v189, v4, v205, v189
	global_store_dwordx4 v214, v[186:189], s[84:85]
	s_nop 1
	v_add_u32_e32 v214, 0x8000, v214
	global_load_dwordx4 v[186:189], v184, s[24:25]
	s_nop 0
	v_add_u32_e32 v184, 0x8000, v184
	s_waitcnt vmcnt(14) lgkmcnt(0)
	v_fma_f32 v190, v26, v210, v190
	v_fma_f32 v191, v2, v211, v191
	v_fma_f32 v192, v28, v212, v192
	v_fma_f32 v193, v4, v213, v193
	global_store_dwordx4 v214, v[190:193], s[84:85]
	s_nop 1
	v_add_u32_e32 v214, 0x8000, v214
	global_load_dwordx4 v[190:193], v184, s[24:25]
	s_nop 0
	v_add_u32_e32 v184, 0x8000, v184
	ds_read_b128 v[194:197], v182 offset:33792
	ds_read_b128 v[198:201], v182 offset:38016
	ds_read_b128 v[202:205], v182 offset:42240
	ds_read_b128 v[210:213], v182 offset:46464
	s_waitcnt vmcnt(14) lgkmcnt(3)
	v_fma_f32 v158, v26, v194, v158
	v_fma_f32 v159, v2, v195, v159
	v_fma_f32 v160, v28, v196, v160
	v_fma_f32 v161, v4, v197, v161
	global_store_dwordx4 v214, v[158:161], s[84:85]
	s_nop 1
	v_add_u32_e32 v214, 0x8000, v214
	s_waitcnt vmcnt(13) lgkmcnt(2)
	v_fma_f32 v162, v26, v198, v162
	v_fma_f32 v163, v2, v199, v163
	v_fma_f32 v164, v28, v200, v164
	v_fma_f32 v165, v4, v201, v165
	global_store_dwordx4 v214, v[162:165], s[84:85]
	s_nop 1
	v_add_u32_e32 v214, 0x8000, v214
	s_waitcnt vmcnt(12) lgkmcnt(1)
	v_fma_f32 v166, v26, v202, v166
	v_fma_f32 v167, v2, v203, v167
	v_fma_f32 v168, v28, v204, v168
	v_fma_f32 v169, v4, v205, v169
	global_store_dwordx4 v214, v[166:169], s[84:85]
	s_nop 1
	v_add_u32_e32 v214, 0x8000, v214
	s_waitcnt vmcnt(11) lgkmcnt(0)
	v_fma_f32 v170, v26, v210, v170
	v_fma_f32 v171, v2, v211, v171
	v_fma_f32 v172, v28, v212, v172
	v_fma_f32 v173, v4, v213, v173
	global_store_dwordx4 v214, v[170:173], s[84:85]
	s_nop 1
	v_add_u32_e32 v214, 0x8000, v214
	ds_read_b128 v[194:197], v182 offset:50688
	ds_read_b128 v[198:201], v182 offset:54912
	ds_read_b128 v[202:205], v182 offset:59136
	ds_read_b128 v[210:213], v182 offset:63360
	s_waitcnt vmcnt(10) lgkmcnt(3)
	v_fma_f32 v174, v26, v194, v174
	v_fma_f32 v175, v2, v195, v175
	v_fma_f32 v176, v28, v196, v176
	v_fma_f32 v177, v4, v197, v177
	global_store_dwordx4 v214, v[174:177], s[84:85]
	s_nop 1
	v_add_u32_e32 v214, 0x8000, v214
	s_waitcnt vmcnt(9) lgkmcnt(2)
	v_fma_f32 v178, v26, v198, v178
	v_fma_f32 v179, v2, v199, v179
	v_fma_f32 v180, v28, v200, v180
	v_fma_f32 v181, v4, v201, v181
	global_store_dwordx4 v214, v[178:181], s[84:85]
	s_nop 1
	v_add_u32_e32 v214, 0x8000, v214
	s_waitcnt vmcnt(8) lgkmcnt(1)
	v_fma_f32 v186, v26, v202, v186
	v_fma_f32 v187, v2, v203, v187
	v_fma_f32 v188, v28, v204, v188
	v_fma_f32 v189, v4, v205, v189
	global_store_dwordx4 v214, v[186:189], s[84:85]
	s_nop 1
	v_add_u32_e32 v214, 0x8000, v214
	s_waitcnt vmcnt(7) lgkmcnt(0)
	v_fma_f32 v190, v26, v210, v190
	v_fma_f32 v191, v2, v211, v191
	v_fma_f32 v192, v28, v212, v192
	v_fma_f32 v193, v4, v213, v193
	global_store_dwordx4 v214, v[190:193], s[84:85]
	s_nop 1
	v_add_u32_e32 v214, 0x8000, v214
	s_barrier
	s_branch .LBB0_1115

; DI int otid() { int t = threadIdx.x; asm volatile("" : "+v"(t)); return t; }
; DI void gemm_res_tile_big(const bf16_t* A, int lda, const bf16_t* Bt, int K, const float* __restrict__ xin, float* __restrict__ xout,
;                           const float* __restrict__ gate, int mt, int nt, char* smem) {
;     ...
;     const int tid = otid();
;     stage_half(st, acc, h, tid);
;     __syncthreads();
;     const int r = tid >> 5, ch = tid & 31;
;     const float4 g = *(const float4*)(gate + (size_t)b * 6144 + n0 + ch * 4);
; #pragma unroll 4
;     for (int ps = 0; ps < 16; ++ps) {
;       const int row = ps * 8 + r;
;       const float4 a = *(const float4*)(st + row * 132 + ch * 4);
;       const size_t off = (size_t)(m0 + h * 128 + row) * 1024 + n0 + ch * 4;
;       const float4 xi = *(const float4*)(xin + off);
;       float4 o; o.x = xi.x + g.x * a.x; o.y = xi.y + g.y * a.y; o.z = xi.z + g.z * a.z; o.w = xi.w + g.w * a.w;
;       *(float4*)(xout + off) = o;
;     }
;     __syncthreads();
.LBB0_1303:
	v_lshrrev_b32_e32 v215, 5, v216
	v_mul_u32_u24_e32 v182, 0x210, v215
	v_and_b32_e32 v215, 31, v216
	v_lshl_add_u32 v182, v215, 4, v182
	v_lshlrev_b32_e32 v184, 10, v136
	v_add_u32_e32 v184, v184, v144
	v_lshlrev_b32_e32 v184, 2, v184
	v_mov_b32_e32 v214, v184
	global_load_dwordx4 v[158:161], v184, s[84:85]
	s_nop 0
	v_add_u32_e32 v184, 0x8000, v184
	global_load_dwordx4 v[162:165], v184, s[84:85]
	s_nop 0
	v_add_u32_e32 v184, 0x8000, v184
	global_load_dwordx4 v[166:169], v184, s[84:85]
	s_nop 0
	v_add_u32_e32 v184, 0x8000, v184
	global_load_dwordx4 v[170:173], v184, s[84:85]
	s_nop 0
	v_add_u32_e32 v184, 0x8000, v184
	global_load_dwordx4 v[174:177], v184, s[84:85]
	s_nop 0
	v_add_u32_e32 v184, 0x8000, v184
	global_load_dwordx4 v[178:181], v184, s[84:85]
	s_nop 0
	v_add_u32_e32 v184, 0x8000, v184
	global_load_dwordx4 v[186:189], v184, s[84:85]
	s_nop 0
	v_add_u32_e32 v184, 0x8000, v184
	global_load_dwordx4 v[190:193], v184, s[84:85]
	s_nop 0
	v_add_u32_e32 v184, 0x8000, v184
	ds_read_b128 v[194:197], v182 offset:0
	ds_read_b128 v[198:201], v182 offset:4224
	ds_read_b128 v[202:205], v182 offset:8448
	ds_read_b128 v[210:213], v182 offset:12672
	s_waitcnt vmcnt(7) lgkmcnt(3)
	v_fma_f32 v158, v154, v194, v158
	v_fma_f32 v159, v130, v195, v159
	v_fma_f32 v160, v156, v196, v160
	v_fma_f32 v161, v132, v197, v161
	global_store_dwordx4 v214, v[158:161], s[0:1]
	s_nop 1
	v_add_u32_e32 v214, 0x8000, v214
	global_load_dwordx4 v[158:161], v184, s[84:85]
	s_nop 0
	v_add_u32_e32 v184, 0x8000, v184
	s_waitcnt vmcnt(8) lgkmcnt(2)
	v_fma_f32 v162, v154, v198, v162
	v_fma_f32 v163, v130, v199, v163
	v_fma_f32 v164, v156, v200, v164
	v_fma_f32 v165, v132, v201, v165
	global_store_dwordx4 v214, v[162:165], s[0:1]
	s_nop 1
	v_add_u32_e32 v214, 0x8000, v214
	global_load_dwordx4 v[162:165], v184, s[84:85]
	s_nop 0
	v_add_u32_e32 v184, 0x8000, v184
	s_waitcnt vmcnt(9) lgkmcnt(1)
	v_fma_f32 v166, v154, v202, v166
	v_fma_f32 v167, v130, v203, v167
	v_fma_f32 v168, v156, v204, v168
	v_fma_f32 v169, v132, v205, v169
	global_store_dwordx4 v214, v[166:169], s[0:1]
	s_nop 1
	v_add_u32_e32 v214, 0x8000, v214
	global_load_dwordx4 v[166:169], v184, s[84:85]
	s_nop 0
	v_add_u32_e32 v184, 0x8000, v184
	s_waitcnt vmcnt(10) lgkmcnt(0)
	v_fma_f32 v170, v154, v210, v170
	v_fma_f32 v171, v130, v211, v171
	v_fma_f32 v172, v156, v212, v172
	v_fma_f32 v173, v132, v213, v173
	global_store_dwordx4 v214, v[170:173], s[0:1]
	s_nop 1
	v_add_u32_e32 v214, 0x8000, v214
	global_load_dwordx4 v[170:173], v184, s[84:85]
	s_nop 0
	v_add_u32_e32 v184, 0x8000, v184
	ds_read_b128 v[194:197], v182 offset:16896
	ds_read_b128 v[198:201], v182 offset:21120
	ds_read_b128 v[202:205], v182 offset:25344
	ds_read_b128 v[210:213], v182 offset:29568
	s_waitcnt vmcnt(11) lgkmcnt(3)
	v_fma_f32 v174, v154, v194, v174
	v_fma_f32 v175, v130, v195, v175
	v_fma_f32 v176, v156, v196, v176
	v_fma_f32 v177, v132, v197, v177
	global_store_dwordx4 v214, v[174:177], s[0:1]
	s_nop 1
	v_add_u32_e32 v214, 0x8000, v214
	global_load_dwordx4 v[174:177], v184, s[84:85]
	s_nop 0
	v_add_u32_e32 v184, 0x8000, v184
	s_waitcnt vmcnt(12) lgkmcnt(2)
	v_fma_f32 v178, v154, v198, v178
	v_fma_f32 v179, v130, v199, v179
	v_fma_f32 v180, v156, v200, v180
	v_fma_f32 v181, v132, v201, v181
	global_store_dwordx4 v214, v[178:181], s[0:1]
	s_nop 1
	v_add_u32_e32 v214, 0x8000, v214
	global_load_dwordx4 v[178:181], v184, s[84:85]
	s_nop 0
	v_add_u32_e32 v184, 0x8000, v184
	s_waitcnt vmcnt(13) lgkmcnt(1)
	v_fma_f32 v186, v154, v202, v186
	v_fma_f32 v187, v130, v203, v187
	v_fma_f32 v188, v156, v204, v188
	v_fma_f32 v189, v132, v205, v189
	global_store_dwordx4 v214, v[186:189], s[0:1]
	s_nop 1
	v_add_u32_e32 v214, 0x8000, v214
	global_load_dwordx4 v[186:189], v184, s[84:85]
	s_nop 0
	v_add_u32_e32 v184, 0x8000, v184
	s_waitcnt vmcnt(14) lgkmcnt(0)
	v_fma_f32 v190, v154, v210, v190
	v_fma_f32 v191, v130, v211, v191
	v_fma_f32 v192, v156, v212, v192
	v_fma_f32 v193, v132, v213, v193
	global_store_dwordx4 v214, v[190:193], s[0:1]
	s_nop 1
	v_add_u32_e32 v214, 0x8000, v214
	global_load_dwordx4 v[190:193], v184, s[84:85]
	s_nop 0
	v_add_u32_e32 v184, 0x8000, v184
	ds_read_b128 v[194:197], v182 offset:33792
	ds_read_b128 v[198:201], v182 offset:38016
	ds_read_b128 v[202:205], v182 offset:42240
	ds_read_b128 v[210:213], v182 offset:46464
	s_waitcnt vmcnt(14) lgkmcnt(3)
	v_fma_f32 v158, v154, v194, v158
	v_fma_f32 v159, v130, v195, v159
	v_fma_f32 v160, v156, v196, v160
	v_fma_f32 v161, v132, v197, v161
	global_store_dwordx4 v214, v[158:161], s[0:1]
	s_nop 1
	v_add_u32_e32 v214, 0x8000, v214
	s_waitcnt vmcnt(13) lgkmcnt(2)
	v_fma_f32 v162, v154, v198, v162
	v_fma_f32 v163, v130, v199, v163
	v_fma_f32 v164, v156, v200, v164
	v_fma_f32 v165, v132, v201, v165
	global_store_dwordx4 v214, v[162:165], s[0:1]
	s_nop 1
	v_add_u32_e32 v214, 0x8000, v214
	s_waitcnt vmcnt(12) lgkmcnt(1)
	v_fma_f32 v166, v154, v202, v166
	v_fma_f32 v167, v130, v203, v167
	v_fma_f32 v168, v156, v204, v168
	v_fma_f32 v169, v132, v205, v169
	global_store_dwordx4 v214, v[166:169], s[0:1]
	s_nop 1
	v_add_u32_e32 v214, 0x8000, v214
	s_waitcnt vmcnt(11) lgkmcnt(0)
	v_fma_f32 v170, v154, v210, v170
	v_fma_f32 v171, v130, v211, v171
	v_fma_f32 v172, v156, v212, v172
	v_fma_f32 v173, v132, v213, v173
	global_store_dwordx4 v214, v[170:173], s[0:1]
	s_nop 1
	v_add_u32_e32 v214, 0x8000, v214
	ds_read_b128 v[194:197], v182 offset:50688
	ds_read_b128 v[198:201], v182 offset:54912
	ds_read_b128 v[202:205], v182 offset:59136
	ds_read_b128 v[210:213], v182 offset:63360
	s_waitcnt vmcnt(10) lgkmcnt(3)
	v_fma_f32 v174, v154, v194, v174
	v_fma_f32 v175, v130, v195, v175
	v_fma_f32 v176, v156, v196, v176
	v_fma_f32 v177, v132, v197, v177
	global_store_dwordx4 v214, v[174:177], s[0:1]
	s_nop 1
	v_add_u32_e32 v214, 0x8000, v214
	s_waitcnt vmcnt(9) lgkmcnt(2)
	v_fma_f32 v178, v154, v198, v178
	v_fma_f32 v179, v130, v199, v179
	v_fma_f32 v180, v156, v200, v180
	v_fma_f32 v181, v132, v201, v181
	global_store_dwordx4 v214, v[178:181], s[0:1]
	s_nop 1
	v_add_u32_e32 v214, 0x8000, v214
	s_waitcnt vmcnt(8) lgkmcnt(1)
	v_fma_f32 v186, v154, v202, v186
	v_fma_f32 v187, v130, v203, v187
	v_fma_f32 v188, v156, v204, v188
	v_fma_f32 v189, v132, v205, v189
	global_store_dwordx4 v214, v[186:189], s[0:1]
	s_nop 1
	v_add_u32_e32 v214, 0x8000, v214
	s_waitcnt vmcnt(7) lgkmcnt(0)
	v_fma_f32 v190, v154, v210, v190
	v_fma_f32 v191, v130, v211, v191
	v_fma_f32 v192, v156, v212, v192
	v_fma_f32 v193, v132, v213, v193
	global_store_dwordx4 v214, v[190:193], s[0:1]
	s_nop 1
	v_add_u32_e32 v214, 0x8000, v214
	v_mov_b32_e32 v130, v216
	s_barrier
; DI int crow(int i, int h) { return (i & 3) + 8 * (i >> 2) + 4 * h; }
; DI void stage_half(float* st, const f32x16 (&acc)[4][2], int h, int tid) {
;   const int lane = tid & 63, w = tid >> 6, wm = w >> 1, wn = w & 1, c = lane & 31, half = lane >> 5;
;   if (wm == h) {
; #pragma unroll
;     for (int mf = 0; mf < 4; ++mf)
; #pragma unroll
;       for (int nf = 0; nf < 2; ++nf)
; #pragma unroll
;         for (int i = 0; i < 16; ++i) st[(mf * 32 + crow(i, half)) * 132 + wn * 64 + nf * 32 + c] = acc[mf][nf][i];
;   }
; }
	s_nop 0
	v_and_b32_e32 v0, 0xffffff80, v130
	v_cmp_eq_u32_e32 vcc, s31, v0
	s_and_saveexec_b64 s[42:43], vcc
	s_cbranch_execz .LBB0_1306
	v_lshrrev_b32_e32 v0, 3, v130
	v_and_b32_e32 v0, 4, v0
	v_and_b32_e32 v131, 0x5f, v130
	v_mul_u32_u24_e32 v0, 0x210, v0
	v_lshl_add_u32 v0, v131, 2, v0
	ds_write2_b32 v0, v114, v98 offset1:32
	ds_write2_b32 v0, v115, v99 offset0:132 offset1:164
	v_add_u32_e32 v98, 0x400, v0
	ds_write2_b32 v98, v116, v100 offset0:8 offset1:40
	ds_write2_b32 v98, v117, v101 offset0:140 offset1:172
	v_add_u32_e32 v98, 0x1000, v0
	ds_write2_b32 v98, v118, v102 offset0:32 offset1:64
	ds_write2_b32 v98, v119, v103 offset0:164 offset1:196
	v_add_u32_e32 v98, 0x1400, v0
	ds_write2_b32 v98, v120, v104 offset0:40 offset1:72
	ds_write2_b32 v98, v121, v105 offset0:172 offset1:204
	v_add_u32_e32 v98, 0x2000, v0
	ds_write2_b32 v98, v122, v106 offset0:64 offset1:96
	ds_write2_b32 v98, v123, v107 offset0:196 offset1:228
	v_add_u32_e32 v98, 0x2400, v0
	ds_write2_b32 v98, v124, v108 offset0:72 offset1:104
	ds_write2_b32 v98, v125, v109 offset0:204 offset1:236
	v_add_u32_e32 v98, 0x3000, v0
	ds_write2_b32 v98, v126, v110 offset0:96 offset1:128
	v_add_u32_e32 v98, 0x3200, v0
	ds_write2_b32 v98, v127, v111 offset0:100 offset1:132
	v_add_u32_e32 v98, 0x3400, v0
	ds_write2_b32 v98, v128, v112 offset0:104 offset1:136
	v_add_u32_e32 v98, 0x3600, v0
	ds_write2_b32 v98, v129, v113 offset0:108 offset1:140
	v_add_u32_e32 v98, 0x4000, v0
	ds_write2_b32 v98, v82, v66 offset0:128 offset1:160
	v_add_u32_e32 v66, 0x4400, v0
	ds_write2_b32 v66, v83, v67 offset0:4 offset1:36
	ds_write2_b32 v66, v84, v68 offset0:136 offset1:168
	v_add_u32_e32 v66, 0x4800, v0
	ds_write2_b32 v66, v85, v69 offset0:12 offset1:44
	v_add_u32_e32 v66, 0x5000, v0
	ds_write2_b32 v66, v86, v70 offset0:160 offset1:192
	v_add_u32_e32 v66, 0x5400, v0
	ds_write2_b32 v66, v87, v71 offset0:36 offset1:68
	ds_write2_b32 v66, v88, v72 offset0:168 offset1:200
	v_add_u32_e32 v66, 0x5800, v0
	ds_write2_b32 v66, v89, v73 offset0:44 offset1:76
	v_add_u32_e32 v66, 0x6000, v0
	ds_write2_b32 v66, v90, v74 offset0:192 offset1:224
	v_add_u32_e32 v66, 0x6400, v0
	ds_write2_b32 v66, v91, v75 offset0:68 offset1:100
	ds_write2_b32 v66, v92, v76 offset0:200 offset1:232
	v_add_u32_e32 v66, 0x6800, v0
	ds_write2_b32 v66, v93, v77 offset0:76 offset1:108
	v_add_u32_e32 v66, 0x7200, v0
	ds_write2_b32 v66, v94, v78 offset0:96 offset1:128
	v_add_u32_e32 v66, 0x7400, v0
	ds_write2_b32 v66, v95, v79 offset0:100 offset1:132
	v_add_u32_e32 v66, 0x7600, v0
	ds_write2_b32 v66, v96, v80 offset0:104 offset1:136
	v_add_u32_e32 v66, 0x7800, v0
	ds_write2_b32 v66, v97, v81 offset0:108 offset1:140
	v_add_u32_e32 v66, 0x8400, v0
	ds_write2_b32 v66, v50, v34 offset1:32
	ds_write2_b32 v66, v51, v35 offset0:132 offset1:164
	v_add_u32_e32 v34, 0x8800, v0
	ds_write2_b32 v34, v52, v36 offset0:8 offset1:40
	ds_write2_b32 v34, v53, v37 offset0:140 offset1:172
	v_add_u32_e32 v34, 0x9400, v0
	ds_write2_b32 v34, v54, v38 offset0:32 offset1:64
	ds_write2_b32 v34, v55, v39 offset0:164 offset1:196
	v_add_u32_e32 v34, 0x9800, v0
	ds_write2_b32 v34, v56, v40 offset0:40 offset1:72
	ds_write2_b32 v34, v57, v41 offset0:172 offset1:204
	v_add_u32_e32 v34, 0xa400, v0
	ds_write2_b32 v34, v58, v42 offset0:64 offset1:96
	ds_write2_b32 v34, v59, v43 offset0:196 offset1:228
	v_add_u32_e32 v34, 0xa800, v0
	ds_write2_b32 v34, v60, v44 offset0:72 offset1:104
	ds_write2_b32 v34, v61, v45 offset0:204 offset1:236
	v_add_u32_e32 v34, 0xb400, v0
	ds_write2_b32 v34, v62, v46 offset0:96 offset1:128
	v_add_u32_e32 v34, 0xb600, v0
	ds_write2_b32 v34, v63, v47 offset0:100 offset1:132
	v_add_u32_e32 v34, 0xb800, v0
	ds_write2_b32 v34, v64, v48 offset0:104 offset1:136
	v_add_u32_e32 v34, 0xba00, v0
	ds_write2_b32 v34, v65, v49 offset0:108 offset1:140
	v_add_u32_e32 v34, 0xc400, v0
	ds_write2_b32 v34, v18, v2 offset0:128 offset1:160
	v_add_u32_e32 v2, 0xc800, v0
	ds_write2_b32 v2, v19, v3 offset0:4 offset1:36
	ds_write2_b32 v2, v20, v4 offset0:136 offset1:168
	v_add_u32_e32 v2, 0xcc00, v0
	ds_write2_b32 v2, v21, v5 offset0:12 offset1:44
	v_add_u32_e32 v2, 0xd400, v0
	ds_write2_b32 v2, v22, v6 offset0:160 offset1:192
	v_add_u32_e32 v2, 0xd800, v0
	ds_write2_b32 v2, v23, v7 offset0:36 offset1:68
	ds_write2_b32 v2, v24, v8 offset0:168 offset1:200
	v_add_u32_e32 v2, 0xdc00, v0
	ds_write2_b32 v2, v25, v9 offset0:44 offset1:76
	v_add_u32_e32 v2, 0xe400, v0
	ds_write2_b32 v2, v26, v10 offset0:192 offset1:224
	v_add_u32_e32 v2, 0xe800, v0
	ds_write2_b32 v2, v27, v11 offset0:68 offset1:100
	ds_write2_b32 v2, v28, v12 offset0:200 offset1:232
	v_add_u32_e32 v2, 0xec00, v0
	ds_write2_b32 v2, v29, v13 offset0:76 offset1:108
	v_add_u32_e32 v2, 0xf600, v0
	ds_write2_b32 v2, v30, v14 offset0:96 offset1:128
	v_add_u32_e32 v2, 0xf800, v0
	ds_write2_b32 v2, v31, v15 offset0:100 offset1:132
	v_add_u32_e32 v2, 0xfa00, v0
	v_add_u32_e32 v0, 0xfc00, v0
	ds_write2_b32 v2, v32, v16 offset0:104 offset1:136
	ds_write2_b32 v0, v33, v17 offset0:108 offset1:140

; DI void gemm_res_tile_big(const bf16_t* A, int lda, const bf16_t* Bt, int K, const float* __restrict__ xin, float* __restrict__ xout,
;                           const float* __restrict__ gate, int mt, int nt, char* smem) {
;     ...
;     const int r = tid >> 5, ch = tid & 31;
;     const float4 g = *(const float4*)(gate + (size_t)b * 6144 + n0 + ch * 4);
; #pragma unroll 4
;     for (int ps = 0; ps < 16; ++ps) {
;       const int row = ps * 8 + r;
;       const float4 a = *(const float4*)(st + row * 132 + ch * 4);
;       const size_t off = (size_t)(m0 + h * 128 + row) * 1024 + n0 + ch * 4;
;       const float4 xi = *(const float4*)(xin + off);
;       float4 o; o.x = xi.x + g.x * a.x; o.y = xi.y + g.y * a.y; o.z = xi.z + g.z * a.z; o.w = xi.w + g.w * a.w;
;       *(float4*)(xout + off) = o;
;     }
.LBB0_1307:
	v_lshrrev_b32_e32 v215, 5, v216
	v_mul_u32_u24_e32 v182, 0x210, v215
	v_and_b32_e32 v215, 31, v216
	v_lshl_add_u32 v182, v215, 4, v182
	v_lshlrev_b32_e32 v184, 10, v12
	v_add_u32_e32 v184, v184, v8
	v_lshlrev_b32_e32 v184, 2, v184
	v_mov_b32_e32 v214, v184
	global_load_dwordx4 v[158:161], v184, s[84:85]
	s_nop 0
	v_add_u32_e32 v184, 0x8000, v184
	global_load_dwordx4 v[162:165], v184, s[84:85]
	s_nop 0
	v_add_u32_e32 v184, 0x8000, v184
	global_load_dwordx4 v[166:169], v184, s[84:85]
	s_nop 0
	v_add_u32_e32 v184, 0x8000, v184
	global_load_dwordx4 v[170:173], v184, s[84:85]
	s_nop 0
	v_add_u32_e32 v184, 0x8000, v184
	global_load_dwordx4 v[174:177], v184, s[84:85]
	s_nop 0
	v_add_u32_e32 v184, 0x8000, v184
	global_load_dwordx4 v[178:181], v184, s[84:85]
	s_nop 0
	v_add_u32_e32 v184, 0x8000, v184
	global_load_dwordx4 v[186:189], v184, s[84:85]
	s_nop 0
	v_add_u32_e32 v184, 0x8000, v184
	global_load_dwordx4 v[190:193], v184, s[84:85]
	s_nop 0
	v_add_u32_e32 v184, 0x8000, v184
	ds_read_b128 v[194:197], v182 offset:0
	ds_read_b128 v[198:201], v182 offset:4224
	ds_read_b128 v[202:205], v182 offset:8448
	ds_read_b128 v[210:213], v182 offset:12672
	s_waitcnt vmcnt(7) lgkmcnt(3)
	v_fma_f32 v158, v26, v194, v158
	v_fma_f32 v159, v2, v195, v159
	v_fma_f32 v160, v28, v196, v160
	v_fma_f32 v161, v4, v197, v161
	global_store_dwordx4 v214, v[158:161], s[0:1]
	s_nop 1
	v_add_u32_e32 v214, 0x8000, v214
	global_load_dwordx4 v[158:161], v184, s[84:85]
	s_nop 0
	v_add_u32_e32 v184, 0x8000, v184
	s_waitcnt vmcnt(8) lgkmcnt(2)
	v_fma_f32 v162, v26, v198, v162
	v_fma_f32 v163, v2, v199, v163
	v_fma_f32 v164, v28, v200, v164
	v_fma_f32 v165, v4, v201, v165
	global_store_dwordx4 v214, v[162:165], s[0:1]
	s_nop 1
	v_add_u32_e32 v214, 0x8000, v214
	global_load_dwordx4 v[162:165], v184, s[84:85]
	s_nop 0
	v_add_u32_e32 v184, 0x8000, v184
	s_waitcnt vmcnt(9) lgkmcnt(1)
	v_fma_f32 v166, v26, v202, v166
	v_fma_f32 v167, v2, v203, v167
	v_fma_f32 v168, v28, v204, v168
	v_fma_f32 v169, v4, v205, v169
	global_store_dwordx4 v214, v[166:169], s[0:1]
	s_nop 1
	v_add_u32_e32 v214, 0x8000, v214
	global_load_dwordx4 v[166:169], v184, s[84:85]
	s_nop 0
	v_add_u32_e32 v184, 0x8000, v184
	s_waitcnt vmcnt(10) lgkmcnt(0)
	v_fma_f32 v170, v26, v210, v170
	v_fma_f32 v171, v2, v211, v171
	v_fma_f32 v172, v28, v212, v172
	v_fma_f32 v173, v4, v213, v173
	global_store_dwordx4 v214, v[170:173], s[0:1]
	s_nop 1
	v_add_u32_e32 v214, 0x8000, v214
	global_load_dwordx4 v[170:173], v184, s[84:85]
	s_nop 0
	v_add_u32_e32 v184, 0x8000, v184
	ds_read_b128 v[194:197], v182 offset:16896
	ds_read_b128 v[198:201], v182 offset:21120
	ds_read_b128 v[202:205], v182 offset:25344
	ds_read_b128 v[210:213], v182 offset:29568
	s_waitcnt vmcnt(11) lgkmcnt(3)
	v_fma_f32 v174, v26, v194, v174
	v_fma_f32 v175, v2, v195, v175
	v_fma_f32 v176, v28, v196, v176
	v_fma_f32 v177, v4, v197, v177
	global_store_dwordx4 v214, v[174:177], s[0:1]
	s_nop 1
	v_add_u32_e32 v214, 0x8000, v214
	global_load_dwordx4 v[174:177], v184, s[84:85]
	s_nop 0
	v_add_u32_e32 v184, 0x8000, v184
	s_waitcnt vmcnt(12) lgkmcnt(2)
	v_fma_f32 v178, v26, v198, v178
	v_fma_f32 v179, v2, v199, v179
	v_fma_f32 v180, v28, v200, v180
	v_fma_f32 v181, v4, v201, v181
	global_store_dwordx4 v214, v[178:181], s[0:1]
	s_nop 1
	v_add_u32_e32 v214, 0x8000, v214
	global_load_dwordx4 v[178:181], v184, s[84:85]
	s_nop 0
	v_add_u32_e32 v184, 0x8000, v184
	s_waitcnt vmcnt(13) lgkmcnt(1)
	v_fma_f32 v186, v26, v202, v186
	v_fma_f32 v187, v2, v203, v187
	v_fma_f32 v188, v28, v204, v188
	v_fma_f32 v189, v4, v205, v189
	global_store_dwordx4 v214, v[186:189], s[0:1]
	s_nop 1
	v_add_u32_e32 v214, 0x8000, v214
	global_load_dwordx4 v[186:189], v184, s[84:85]
	s_nop 0
	v_add_u32_e32 v184, 0x8000, v184
	s_waitcnt vmcnt(14) lgkmcnt(0)
	v_fma_f32 v190, v26, v210, v190
	v_fma_f32 v191, v2, v211, v191
	v_fma_f32 v192, v28, v212, v192
	v_fma_f32 v193, v4, v213, v193
	global_store_dwordx4 v214, v[190:193], s[0:1]
	s_nop 1
	v_add_u32_e32 v214, 0x8000, v214
	global_load_dwordx4 v[190:193], v184, s[84:85]
	s_nop 0
	v_add_u32_e32 v184, 0x8000, v184
	ds_read_b128 v[194:197], v182 offset:33792
	ds_read_b128 v[198:201], v182 offset:38016
	ds_read_b128 v[202:205], v182 offset:42240
	ds_read_b128 v[210:213], v182 offset:46464
	s_waitcnt vmcnt(14) lgkmcnt(3)
	v_fma_f32 v158, v26, v194, v158
	v_fma_f32 v159, v2, v195, v159
	v_fma_f32 v160, v28, v196, v160
	v_fma_f32 v161, v4, v197, v161
	global_store_dwordx4 v214, v[158:161], s[0:1]
	s_nop 1
	v_add_u32_e32 v214, 0x8000, v214
	s_waitcnt vmcnt(13) lgkmcnt(2)
	v_fma_f32 v162, v26, v198, v162
	v_fma_f32 v163, v2, v199, v163
	v_fma_f32 v164, v28, v200, v164
	v_fma_f32 v165, v4, v201, v165
	global_store_dwordx4 v214, v[162:165], s[0:1]
	s_nop 1
	v_add_u32_e32 v214, 0x8000, v214
	s_waitcnt vmcnt(12) lgkmcnt(1)
	v_fma_f32 v166, v26, v202, v166
	v_fma_f32 v167, v2, v203, v167
	v_fma_f32 v168, v28, v204, v168
	v_fma_f32 v169, v4, v205, v169
	global_store_dwordx4 v214, v[166:169], s[0:1]
	s_nop 1
	v_add_u32_e32 v214, 0x8000, v214
	s_waitcnt vmcnt(11) lgkmcnt(0)
	v_fma_f32 v170, v26, v210, v170
	v_fma_f32 v171, v2, v211, v171
	v_fma_f32 v172, v28, v212, v172
	v_fma_f32 v173, v4, v213, v173
	global_store_dwordx4 v214, v[170:173], s[0:1]
	s_nop 1
	v_add_u32_e32 v214, 0x8000, v214
	ds_read_b128 v[194:197], v182 offset:50688
	ds_read_b128 v[198:201], v182 offset:54912
	ds_read_b128 v[202:205], v182 offset:59136
	ds_read_b128 v[210:213], v182 offset:63360
	s_waitcnt vmcnt(10) lgkmcnt(3)
	v_fma_f32 v174, v26, v194, v174
	v_fma_f32 v175, v2, v195, v175
	v_fma_f32 v176, v28, v196, v176
	v_fma_f32 v177, v4, v197, v177
	global_store_dwordx4 v214, v[174:177], s[0:1]
	s_nop 1
	v_add_u32_e32 v214, 0x8000, v214
	s_waitcnt vmcnt(9) lgkmcnt(2)
	v_fma_f32 v178, v26, v198, v178
	v_fma_f32 v179, v2, v199, v179
	v_fma_f32 v180, v28, v200, v180
	v_fma_f32 v181, v4, v201, v181
	global_store_dwordx4 v214, v[178:181], s[0:1]
	s_nop 1
	v_add_u32_e32 v214, 0x8000, v214
	s_waitcnt vmcnt(8) lgkmcnt(1)
	v_fma_f32 v186, v26, v202, v186
	v_fma_f32 v187, v2, v203, v187
	v_fma_f32 v188, v28, v204, v188
	v_fma_f32 v189, v4, v205, v189
	global_store_dwordx4 v214, v[186:189], s[0:1]
	s_nop 1
	v_add_u32_e32 v214, 0x8000, v214
	s_waitcnt vmcnt(7) lgkmcnt(0)
	v_fma_f32 v190, v26, v210, v190
	v_fma_f32 v191, v2, v211, v191
	v_fma_f32 v192, v28, v212, v192
	v_fma_f32 v193, v4, v213, v193
	global_store_dwordx4 v214, v[190:193], s[0:1]
	s_nop 1
	v_add_u32_e32 v214, 0x8000, v214
	s_barrier
	s_branch .LBB0_1296
